# GEMM tile scheduler: division by group size (always 8) in the unit head replaced by shift/and, removing a v_rcp->readfirstlane chain per tile
# speedup vs baseline: 1.0008x; 1.0008x over previous
;     __device__ bool next(int i, Unit& u) const { if (!so.next(i >> 1, u)) return false; u.kind = i & 1; return true; }
;     __device__ bool next(int i, Unit& u) const {
;         const long L = (long)i * G + c; if (L >= nwg) return false;
;         int wgid = (int)L; { const int q = nwg / NXCD, r = nwg % NXCD, xcd = wgid % NXCD, off = wgid / NXCD; wgid = (xcd < r ? xcd * (q + 1) : r * (q + 1) + (xcd - r) * q) + off; }
;         const int nig = WGM * nN, gid = wgid / nig, fm = gid * WGM, gsz = (nM - fm) < WGM ? (nM - fm) : WGM;
;         u.pm = fm + ((wgid % nig) % gsz); u.pn = (wgid % nig) / gsz; u.kind = 0; return true;
.LBB0_91:
	s_add_i32 s31, s31, 1
	s_mul_i32 s0, s31, s3
	s_mul_hi_u32 s1, s31, s82
	s_add_i32 s1, s1, s0
	s_mul_i32 s0, s31, s82
	s_add_u32 s18, s0, s2
	s_addc_u32 s19, s1, s33
	v_cmp_gt_i64_e32 vcc, s[18:19], v[182:183]
	v_cmp_lt_i64_e64 s[0:1], s[18:19], v[180:181]
	s_cbranch_vccnz .LBB0_93
	s_ashr_i32 s14, s18, 31
	s_lshr_b32 s14, s14, 29
	s_add_i32 s14, s18, s14
	s_ashr_i32 s15, s14, 3
	s_and_b32 s14, s14, -8
	s_sub_i32 s14, s18, s14
	s_cmp_lt_i32 s14, 0
	s_cselect_b32 s16, s85, 0xb0
	s_mul_i32 s14, s14, s16
	s_add_i32 s14, s14, s15
	s_mul_hi_i32 s15, s14, 0x2e8ba2e9
	s_lshr_b32 s16, s15, 31
	s_ashr_i32 s15, s15, 6
	s_add_i32 s15, s15, s16
	s_lshl_b32 s16, s15, 3
	s_sub_i32 s17, 32, s16
	s_min_i32 s17, s17, 8
	s_abs_i32 s18, s17
	s_mulk_i32 s15, 0x160
	s_sub_i32 s15, s14, s15
	s_ashr_i32 s14, s15, 3
	s_and_b32 s15, s15, 7
	s_add_i32 s16, s16, s15

;     __device__ bool next(int i, Unit& u) const { if (!so.next(i >> 1, u)) return false; u.kind = i & 1; return true; }
;     __device__ bool next(int i, Unit& u) const {
;         const long L = (long)i * G + c; if (L >= nwg) return false;
;         int wgid = (int)L; { const int q = nwg / NXCD, r = nwg % NXCD, xcd = wgid % NXCD, off = wgid / NXCD; wgid = (xcd < r ? xcd * (q + 1) : r * (q + 1) + (xcd - r) * q) + off; }
;         const int nig = WGM * nN, gid = wgid / nig, fm = gid * WGM, gsz = (nM - fm) < WGM ? (nM - fm) : WGM;
;         u.pm = fm + ((wgid % nig) % gsz); u.pn = (wgid % nig) / gsz; u.kind = 0; return true;
.LBB0_180:
	s_ashr_i32 s8, s12, 3
	s_add_i32 s8, s14, s8
	s_ashr_i32 s9, s8, 31
	s_lshr_b32 s9, s9, 26
	s_add_i32 s9, s8, s9
	s_ashr_i32 s12, s9, 6
	s_lshl_b32 s12, s12, 3
	s_sub_i32 s13, 32, s12
	s_min_i32 s13, s13, 8
	s_abs_i32 s14, s13
	s_andn2_b32 s9, s9, 63
	s_sub_i32 s8, s8, s9
	s_ashr_i32 s97, s8, 3
	s_and_b32 s8, s8, 7
	s_add_i32 s85, s12, s8

;     __device__ bool next(int i, Unit& u) const { if (!so.next(i >> 1, u)) return false; u.kind = i & 1; return true; }
;     __device__ bool next(int i, Unit& u) const {
;         const long L = (long)i * G + c; if (L >= nwg) return false;
;         int wgid = (int)L; { const int q = nwg / NXCD, r = nwg % NXCD, xcd = wgid % NXCD, off = wgid / NXCD; wgid = (xcd < r ? xcd * (q + 1) : r * (q + 1) + (xcd - r) * q) + off; }
;         const int nig = WGM * nN, gid = wgid / nig, fm = gid * WGM, gsz = (nM - fm) < WGM ? (nM - fm) : WGM;
;         u.pm = fm + ((wgid % nig) % gsz); u.pn = (wgid % nig) / gsz; u.kind = 0; return true;
.LBB0_303:
	s_add_i32 s35, s35, 1
	s_mul_i32 s7, s35, s3
	s_mul_hi_u32 s9, s35, s82
	s_add_i32 s9, s9, s7
	s_mul_i32 s7, s35, s82
	s_add_u32 s12, s7, s2
	s_addc_u32 s13, s9, s33
	v_cmp_gt_i64_e32 vcc, s[12:13], v[190:191]
	v_cmp_lt_i64_e64 s[10:11], s[12:13], v[188:189]
	s_cbranch_vccnz .LBB0_305
	s_ashr_i32 s6, s12, 31
	s_lshr_b32 s6, s6, 29
	s_add_i32 s6, s12, s6
	s_ashr_i32 s7, s6, 3
	s_and_b32 s6, s6, -8
	s_sub_i32 s6, s12, s6
	s_cmp_lt_i32 s6, 0
	s_cselect_b32 s8, s76, 0xa8
	s_mul_i32 s6, s6, s8
	s_add_i32 s6, s6, s7
	s_mul_hi_i32 s7, s6, 0x30c30c31
	s_lshr_b32 s8, s7, 31
	s_ashr_i32 s7, s7, 6
	s_add_i32 s7, s7, s8
	s_lshl_b32 s8, s7, 3
	s_sub_i32 s9, 32, s8
	s_min_i32 s9, s9, 8
	s_abs_i32 s12, s9
	s_mulk_i32 s7, 0x150
	s_sub_i32 s7, s6, s7
	s_ashr_i32 s6, s7, 3
	s_and_b32 s7, s7, 7
	s_add_i32 s8, s8, s7

;     __device__ bool next(int i, Unit& u) const {
;         const long L = (long)i * G + c; if (L >= nwg) return false;
;         int wgid = (int)L; { const int q = nwg / NXCD, r = nwg % NXCD, xcd = wgid % NXCD, off = wgid / NXCD; wgid = (xcd < r ? xcd * (q + 1) : r * (q + 1) + (xcd - r) * q) + off; }
;         const int nig = WGM * nN, gid = wgid / nig, fm = gid * WGM, gsz = (nM - fm) < WGM ? (nM - fm) : WGM;
;         u.pm = fm + ((wgid % nig) % gsz); u.pn = (wgid % nig) / gsz; u.kind = 0; return true;
;     __device__ bool next(int i, Unit& u) const { if (!so.next(i >> 1, u)) return false; u.kind = i & 1; return true; }
.LBB0_615:
	s_ashr_i32 s8, s15, 3
	s_add_i32 s8, s19, s8
	s_ashr_i32 s9, s8, 31
	s_lshr_b32 s9, s9, 26
	s_add_i32 s9, s8, s9
	s_ashr_i32 s15, s9, 6
	s_lshl_b32 s15, s15, 3
	s_sub_i32 s18, 32, s15
	s_min_i32 s19, s18, 8
	s_abs_i32 s18, s19
	s_andn2_b32 s9, s9, 63
	s_sub_i32 s8, s8, s9
	s_ashr_i32 s18, s8, 3
	s_and_b32 s8, s8, 7
	s_add_i32 s20, s15, s8
	s_and_b32 s76, s75, 1

;     __device__ bool next(int i, Unit& u) const { if (!so.next(i >> 1, u)) return false; u.kind = i & 1; return true; }
;     __device__ bool next(int i, Unit& u) const {
;         const long L = (long)i * G + c; if (L >= nwg) return false;
;         int wgid = (int)L; { const int q = nwg / NXCD, r = nwg % NXCD, xcd = wgid % NXCD, off = wgid / NXCD; wgid = (xcd < r ? xcd * (q + 1) : r * (q + 1) + (xcd - r) * q) + off; }
;         const int nig = WGM * nN, gid = wgid / nig, fm = gid * WGM, gsz = (nM - fm) < WGM ? (nM - fm) : WGM;
;         u.pm = fm + ((wgid % nig) % gsz); u.pn = (wgid % nig) / gsz; u.kind = 0; return true;
.LBB0_785:
	s_ashr_i32 s8, s14, 3
	s_add_i32 s8, s16, s8
	s_ashr_i32 s9, s8, 31
	s_lshr_b32 s9, s9, 26
	s_add_i32 s9, s8, s9
	s_ashr_i32 s14, s9, 6
	s_lshl_b32 s14, s14, 3
	s_sub_i32 s15, 32, s14
	s_min_i32 s15, s15, 8
	s_abs_i32 s16, s15
	s_andn2_b32 s9, s9, 63
	s_sub_i32 s9, s8, s9
	s_ashr_i32 s8, s9, 3
	s_and_b32 s9, s9, 7
	s_add_i32 s14, s14, s9

;     __device__ bool next(int i, Unit& u) const { if (!so.next(i >> 1, u)) return false; u.kind = i & 1; return true; }
;     __device__ bool next(int i, Unit& u) const {
;         const long L = (long)i * G + c; if (L >= nwg) return false;
;         int wgid = (int)L; { const int q = nwg / NXCD, r = nwg % NXCD, xcd = wgid % NXCD, off = wgid / NXCD; wgid = (xcd < r ? xcd * (q + 1) : r * (q + 1) + (xcd - r) * q) + off; }
;         const int nig = WGM * nN, gid = wgid / nig, fm = gid * WGM, gsz = (nM - fm) < WGM ? (nM - fm) : WGM;
;         u.pm = fm + ((wgid % nig) % gsz); u.pn = (wgid % nig) / gsz; u.kind = 0; return true;
.LBB0_868:
	s_add_i32 s35, s35, 1
	s_mul_i32 s8, s35, s3
	s_mul_hi_u32 s9, s35, s82
	s_add_i32 s9, s9, s8
	s_mul_i32 s8, s35, s82
	s_add_u32 s18, s8, s2
	s_addc_u32 s19, s9, s33
	v_cmp_gt_i64_e32 vcc, s[18:19], v[182:183]
	v_cmp_lt_i64_e64 s[8:9], s[18:19], v[180:181]
	s_cbranch_vccnz .LBB0_870
	s_ashr_i32 s14, s18, 31
	s_lshr_b32 s14, s14, 29
	s_add_i32 s14, s18, s14
	s_ashr_i32 s15, s14, 3
	s_and_b32 s14, s14, -8
	s_sub_i32 s14, s18, s14
	s_cmp_lt_i32 s14, 0
	s_cselect_b32 s16, s85, 0xb0
	s_mul_i32 s14, s14, s16
	s_add_i32 s14, s14, s15
	s_mul_hi_i32 s15, s14, 0x2e8ba2e9
	s_lshr_b32 s16, s15, 31
	s_ashr_i32 s15, s15, 6
	s_add_i32 s15, s15, s16
	s_lshl_b32 s16, s15, 3
	s_sub_i32 s17, 32, s16
	s_min_i32 s17, s17, 8
	s_abs_i32 s18, s17
	s_mulk_i32 s15, 0x160
	s_sub_i32 s15, s14, s15
	s_ashr_i32 s14, s15, 3
	s_and_b32 s15, s15, 7
	s_add_i32 s16, s16, s15

;     __device__ bool next(int i, Unit& u) const { if (!so.next(i >> 1, u)) return false; u.kind = i & 1; return true; }
;     __device__ bool next(int i, Unit& u) const {
;         const long L = (long)i * G + c; if (L >= nwg) return false;
;         int wgid = (int)L; { const int q = nwg / NXCD, r = nwg % NXCD, xcd = wgid % NXCD, off = wgid / NXCD; wgid = (xcd < r ? xcd * (q + 1) : r * (q + 1) + (xcd - r) * q) + off; }
;         const int nig = WGM * nN, gid = wgid / nig, fm = gid * WGM, gsz = (nM - fm) < WGM ? (nM - fm) : WGM;
;         u.pm = fm + ((wgid % nig) % gsz); u.pn = (wgid % nig) / gsz; u.kind = 0; return true;
.LBB0_985:
	s_ashr_i32 s4, s14, 3
	s_add_i32 s4, s20, s4
	s_ashr_i32 s5, s4, 31
	s_lshr_b32 s5, s5, 26
	s_add_i32 s5, s4, s5
	s_ashr_i32 s14, s5, 6
	s_lshl_b32 s14, s14, 3
	s_sub_i32 s15, 32, s14
	s_min_i32 s15, s15, 8
	s_abs_i32 s20, s15
	s_andn2_b32 s5, s5, 63
	s_sub_i32 s4, s4, s5
	s_ashr_i32 s70, s4, 3
	s_and_b32 s4, s4, 7
	s_add_i32 s71, s14, s4
